# phase-1 shift@W bias GEMV: the fully serialized load-wait-per-k loop replaced by a rolling window of 16 loads in flight (counted vmcnt waits)
# speedup vs baseline: 1.0092x; 1.0066x over previous
; __device__ __forceinline__ void bias_phase(const Params& P, LAS unsigned char* lds, int G) {
;     ...
;         float a[16];
; #pragma unroll
;         for (int b = 0; b < 16; ++b) a[b] = 0.f;
;         if (j >= 0) { const float* wp = wsrc + (size_t)(wid * 128) * ncol + j;
; #pragma unroll 16
;             for (int k = 0; k < 128; ++k) { const float w = wp[(size_t)k * ncol];
; #pragma unroll
;                 for (int b = 0; b < 16; ++b) a[b] += sC[b * 1024 + wid * 128 + k] * w; } }
.LBB0_649:
	v_mov_b32_e32 v15, 0
	v_cmp_lt_i32_e32 vcc, -1, v0
	v_mov_b32_e32 v14, v15
	v_mov_b32_e32 v19, v15
	v_mov_b32_e32 v18, v15
	v_mov_b32_e32 v23, v15
	v_mov_b32_e32 v22, v15
	v_mov_b32_e32 v27, v15
	v_mov_b32_e32 v26, v15
	v_mov_b32_e32 v29, v15
	v_mov_b32_e32 v28, v15
	v_mov_b32_e32 v21, v15
	v_mov_b32_e32 v20, v15
	v_mov_b32_e32 v17, v15
	v_mov_b32_e32 v16, v15
	v_mov_b32_e32 v25, v15
	v_mov_b32_e32 v24, v15
	s_and_saveexec_b64 s[16:17], vcc
	s_cbranch_execz .LBB0_652
	s_load_dwordx2 s[18:19], s[18:19], 0x0
	s_mul_i32 s11, s34, s8
	s_mul_hi_i32 s9, s34, s8
	s_mul_hi_i32 s35, s14, s49
	s_mul_i32 s34, s14, s49
	s_waitcnt lgkmcnt(0)
	s_add_u32 s11, s18, s11
	s_addc_u32 s9, s19, s9
	s_lshl_b64 s[18:19], s[34:35], 2
	s_add_u32 s18, s11, s18
	s_addc_u32 s19, s9, s19
	v_mov_b32_e32 v24, 0
	v_lshl_add_u64 v[74:75], v[0:1], 2, s[18:19]
	s_mov_b32 s9, 0
	v_mov_b32_e32 v25, v24
	v_mov_b32_e32 v16, v24
	v_mov_b32_e32 v17, v24
	v_mov_b32_e32 v20, v24
	v_mov_b32_e32 v21, v24
	v_mov_b32_e32 v28, v24
	v_mov_b32_e32 v29, v24
	v_mov_b32_e32 v26, v24
	v_mov_b32_e32 v27, v24
	v_mov_b32_e32 v22, v24
	v_mov_b32_e32 v23, v24
	v_mov_b32_e32 v18, v24
	v_mov_b32_e32 v19, v24
	v_mov_b32_e32 v14, v24
	v_mov_b32_e32 v15, v24
	s_mov_b32 s100, s14
	s_mov_b32 s101, 0
	v_mov_b32_e32 v130, v74
	v_mov_b32_e32 v131, v75
	global_load_dword v114, v[130:131], off
	v_lshl_add_u64 v[132:133], s[100:101], 2, v[130:131]
	global_load_dword v115, v[132:133], off
	v_lshl_add_u64 v[134:135], s[100:101], 2, v[132:133]
	global_load_dword v116, v[134:135], off
	v_lshl_add_u64 v[136:137], s[100:101], 2, v[134:135]
	global_load_dword v117, v[136:137], off
	v_lshl_add_u64 v[138:139], s[100:101], 2, v[136:137]
	global_load_dword v118, v[138:139], off
	v_lshl_add_u64 v[140:141], s[100:101], 2, v[138:139]
	global_load_dword v119, v[140:141], off
	v_lshl_add_u64 v[142:143], s[100:101], 2, v[140:141]
	global_load_dword v120, v[142:143], off
	v_lshl_add_u64 v[144:145], s[100:101], 2, v[142:143]
	global_load_dword v121, v[144:145], off
	v_lshl_add_u64 v[146:147], s[100:101], 2, v[144:145]
	global_load_dword v122, v[146:147], off
	v_lshl_add_u64 v[148:149], s[100:101], 2, v[146:147]
	global_load_dword v123, v[148:149], off
	v_lshl_add_u64 v[150:151], s[100:101], 2, v[148:149]
	global_load_dword v124, v[150:151], off
	v_lshl_add_u64 v[152:153], s[100:101], 2, v[150:151]
	global_load_dword v125, v[152:153], off
	v_lshl_add_u64 v[154:155], s[100:101], 2, v[152:153]
	global_load_dword v126, v[154:155], off
	v_lshl_add_u64 v[156:157], s[100:101], 2, v[154:155]
	global_load_dword v127, v[156:157], off
	v_lshl_add_u64 v[158:159], s[100:101], 2, v[156:157]
	global_load_dword v128, v[158:159], off
	v_lshl_add_u64 v[160:161], s[100:101], 2, v[158:159]
	global_load_dword v129, v[160:161], off
.LBB0_651:
	s_lshl_b32 s100, s14, 4
	s_cmpk_eq_i32 s9, 0x70
	s_cselect_b32 s100, 0, s100
	s_mul_hi_u32 s19, s14, s9
	s_mul_i32 s18, s14, s9
	v_lshl_add_u64 v[2:3], s[18:19], 2, v[74:75]
	s_lshl_b32 s11, s9, 2
	s_add_i32 s11, s50, s11
	v_mov_b32_e32 v62, s11
	ds_read_b128 v[38:41], v62 offset:4096
	ds_read_b128 v[42:45], v62 offset:8192
	ds_read_b128 v[46:49], v62 offset:12288
	ds_read_b128 v[34:37], v62 offset:16384
	ds_read_b128 v[50:53], v62 offset:20480
	ds_read_b128 v[54:57], v62 offset:24576
	ds_read_b128 v[58:61], v62 offset:28672
	ds_read_b128 v[30:33], v62 offset:32768
	ds_read_b128 v[76:79], v62 offset:36864
	ds_read_b128 v[80:83], v62 offset:40960
	ds_read_b128 v[84:87], v62 offset:45056
	ds_read_b128 v[88:91], v62 offset:49152
	ds_read_b128 v[98:101], v62 offset:53248
	ds_read_b128 v[102:105], v62 offset:57344
	ds_read_b128 v[106:109], v62 offset:61440
	ds_read_b128 v[110:113], v62
	ds_read_b128 v[10:13], v62 offset:16
	ds_read_b128 v[6:9], v62 offset:32
	ds_read_b128 v[2:5], v62 offset:48
	s_waitcnt lgkmcnt(14)
	v_mov_b32_e32 v65, v38
	s_waitcnt lgkmcnt(3)
	v_mov_b32_e32 v64, v110
	s_or_b32 s11, s9, 1
	s_mul_hi_u32 s19, s14, s11
	s_mul_i32 s18, s14, s11
	s_or_b32 s11, s9, 2
	v_mov_b32_e32 v38, v111
	s_waitcnt vmcnt(15)
	v_mov_b32_e32 v0, v114
	v_lshl_add_u64 v[130:131], s[100:101], 2, v[130:131]
	global_load_dword v114, v[130:131], off
	v_pk_fma_f32 v[24:25], v[0:1], v[64:65], v[24:25] op_sel_hi:[0,1,1]
	v_mov_b32_e32 v64, v42
	v_mov_b32_e32 v65, v46
	v_pk_fma_f32 v[16:17], v[0:1], v[64:65], v[16:17] op_sel_hi:[0,1,1]
	v_mov_b32_e32 v64, v34
	v_mov_b32_e32 v65, v50
	v_pk_fma_f32 v[20:21], v[0:1], v[64:65], v[20:21] op_sel_hi:[0,1,1]
	v_mov_b32_e32 v64, v54
	v_mov_b32_e32 v65, v58
	v_pk_fma_f32 v[28:29], v[0:1], v[64:65], v[28:29] op_sel_hi:[0,1,1]
	v_mov_b32_e32 v64, v30
	v_mov_b32_e32 v65, v76
	v_pk_fma_f32 v[26:27], v[0:1], v[64:65], v[26:27] op_sel_hi:[0,1,1]
	v_mov_b32_e32 v64, v80
	v_mov_b32_e32 v65, v84
	v_pk_fma_f32 v[22:23], v[0:1], v[64:65], v[22:23] op_sel_hi:[0,1,1]
	v_mov_b32_e32 v64, v88
	v_mov_b32_e32 v65, v98
	v_pk_fma_f32 v[18:19], v[0:1], v[64:65], v[18:19] op_sel_hi:[0,1,1]
	v_mov_b32_e32 v64, v102
	v_mov_b32_e32 v65, v106
	v_pk_fma_f32 v[14:15], v[0:1], v[64:65], v[14:15] op_sel_hi:[0,1,1]
	v_lshl_add_u64 v[64:65], s[18:19], 2, v[74:75]
	s_mul_hi_u32 s19, s14, s11
	s_mul_i32 s18, s14, s11
	v_mov_b32_e32 v106, v103
	v_mov_b32_e32 v98, v89
	v_mov_b32_e32 v84, v81
	v_mov_b32_e32 v76, v31
	v_mov_b32_e32 v58, v55
	v_mov_b32_e32 v50, v35
	v_mov_b32_e32 v46, v43
	v_lshl_add_u64 v[30:31], s[18:19], 2, v[74:75]
	s_or_b32 s11, s9, 3
	s_mul_hi_u32 s19, s14, s11
	s_mul_i32 s18, s14, s11
	s_or_b32 s11, s9, 4
	s_waitcnt lgkmcnt(2)
	v_mov_b32_e32 v64, v10
	s_waitcnt vmcnt(15)
; __device__ __forceinline__ void bias_phase(const Params& P, LAS unsigned char* lds, int G) {
;     ...
;         if (j >= 0) { const float* wp = wsrc + (size_t)(wid * 128) * ncol + j;
; #pragma unroll 16
;             for (int k = 0; k < 128; ++k) { const float w = wp[(size_t)k * ncol];
; #pragma unroll
;                 for (int b = 0; b < 16; ++b) a[b] += sC[b * 1024 + wid * 128 + k] * w; } }
	v_mov_b32_e32 v0, v115
	v_lshl_add_u64 v[132:133], s[100:101], 2, v[132:133]
	global_load_dword v115, v[132:133], off
	v_pk_fma_f32 v[14:15], v[0:1], v[106:107], v[14:15] op_sel_hi:[0,1,1]
	v_pk_fma_f32 v[18:19], v[0:1], v[98:99], v[18:19] op_sel_hi:[0,1,1]
	v_pk_fma_f32 v[22:23], v[0:1], v[84:85], v[22:23] op_sel_hi:[0,1,1]
	v_pk_fma_f32 v[26:27], v[0:1], v[76:77], v[26:27] op_sel_hi:[0,1,1]
	v_pk_fma_f32 v[28:29], v[0:1], v[58:59], v[28:29] op_sel_hi:[0,1,1]
	v_pk_fma_f32 v[20:21], v[0:1], v[50:51], v[20:21] op_sel_hi:[0,1,1]
	v_pk_fma_f32 v[16:17], v[0:1], v[46:47], v[16:17] op_sel_hi:[0,1,1]
	v_pk_fma_f32 v[24:25], v[0:1], v[38:39], v[24:25] op_sel_hi:[0,1,1]
	v_mov_b32_e32 v30, v112
	v_mov_b32_e32 v31, v40
	v_mov_b32_e32 v40, v113
	s_waitcnt vmcnt(15)
	v_mov_b32_e32 v0, v116
	v_lshl_add_u64 v[134:135], s[100:101], 2, v[134:135]
	global_load_dword v116, v[134:135], off
	v_pk_fma_f32 v[24:25], v[0:1], v[30:31], v[24:25] op_sel_hi:[0,1,1]
	v_mov_b32_e32 v30, v44
	v_mov_b32_e32 v31, v48
	v_pk_fma_f32 v[16:17], v[0:1], v[30:31], v[16:17] op_sel_hi:[0,1,1]
	v_mov_b32_e32 v30, v36
	v_mov_b32_e32 v31, v52
	v_pk_fma_f32 v[20:21], v[0:1], v[30:31], v[20:21] op_sel_hi:[0,1,1]
	v_mov_b32_e32 v30, v56
	v_mov_b32_e32 v31, v60
	v_pk_fma_f32 v[34:35], v[0:1], v[30:31], v[28:29] op_sel_hi:[0,1,1]
	v_mov_b32_e32 v28, v32
	v_mov_b32_e32 v29, v78
	v_pk_fma_f32 v[38:39], v[0:1], v[28:29], v[26:27] op_sel_hi:[0,1,1]
	v_mov_b32_e32 v26, v82
	v_mov_b32_e32 v27, v86
	v_pk_fma_f32 v[22:23], v[0:1], v[26:27], v[22:23] op_sel_hi:[0,1,1]
	v_mov_b32_e32 v26, v90
	v_mov_b32_e32 v27, v100
	v_pk_fma_f32 v[18:19], v[0:1], v[26:27], v[18:19] op_sel_hi:[0,1,1]
	v_mov_b32_e32 v26, v104
	v_mov_b32_e32 v27, v108
	v_pk_fma_f32 v[14:15], v[0:1], v[26:27], v[14:15] op_sel_hi:[0,1,1]
	v_lshl_add_u64 v[26:27], s[18:19], 2, v[74:75]
	v_mov_b32_e32 v108, v105
	s_mul_hi_u32 s19, s14, s11
	s_mul_i32 s18, s14, s11
	v_mov_b32_e32 v100, v91
	v_mov_b32_e32 v86, v83
	v_mov_b32_e32 v78, v33
	v_mov_b32_e32 v60, v57
	v_mov_b32_e32 v52, v37
	v_mov_b32_e32 v48, v45
	s_or_b32 s11, s9, 5
	s_waitcnt vmcnt(15)
	v_mov_b32_e32 v0, v117
	v_lshl_add_u64 v[136:137], s[100:101], 2, v[136:137]
	global_load_dword v117, v[136:137], off
	v_pk_fma_f32 v[26:27], v[0:1], v[108:109], v[14:15] op_sel_hi:[0,1,1]
	v_lshl_add_u64 v[14:15], s[18:19], 2, v[74:75]
	v_pk_fma_f32 v[28:29], v[0:1], v[100:101], v[18:19] op_sel_hi:[0,1,1]
	v_pk_fma_f32 v[30:31], v[0:1], v[86:87], v[22:23] op_sel_hi:[0,1,1]
	v_pk_fma_f32 v[32:33], v[0:1], v[78:79], v[38:39] op_sel_hi:[0,1,1]
	v_pk_fma_f32 v[34:35], v[0:1], v[60:61], v[34:35] op_sel_hi:[0,1,1]
	v_pk_fma_f32 v[36:37], v[0:1], v[52:53], v[20:21] op_sel_hi:[0,1,1]
	v_pk_fma_f32 v[38:39], v[0:1], v[48:49], v[16:17] op_sel_hi:[0,1,1]
	v_pk_fma_f32 v[40:41], v[0:1], v[40:41], v[24:25] op_sel_hi:[0,1,1]
	ds_read_b128 v[14:17], v62 offset:4112
	ds_read_b128 v[18:21], v62 offset:8208
	ds_read_b128 v[22:25], v62 offset:12304
	ds_read_b128 v[42:45], v62 offset:16400
	ds_read_b128 v[46:49], v62 offset:20496
	ds_read_b128 v[50:53], v62 offset:24592
	ds_read_b128 v[54:57], v62 offset:28688
	ds_read_b128 v[58:61], v62 offset:32784
	ds_read_b128 v[76:79], v62 offset:36880
	ds_read_b128 v[80:83], v62 offset:40976
	ds_read_b128 v[84:87], v62 offset:45072
	ds_read_b128 v[88:91], v62 offset:49168
	ds_read_b128 v[98:101], v62 offset:53264
	ds_read_b128 v[102:105], v62 offset:57360
	ds_read_b128 v[106:109], v62 offset:61456
	s_waitcnt lgkmcnt(14)
	v_mov_b32_e32 v65, v14
	s_mul_hi_u32 s19, s14, s11
	s_mul_i32 s18, s14, s11
	s_or_b32 s11, s9, 6
	v_mov_b32_e32 v14, v11
	s_waitcnt vmcnt(15)
	v_mov_b32_e32 v0, v118
	v_lshl_add_u64 v[138:139], s[100:101], 2, v[138:139]
	global_load_dword v118, v[138:139], off
	v_pk_fma_f32 v[40:41], v[0:1], v[64:65], v[40:41] op_sel_hi:[0,1,1]
	s_waitcnt lgkmcnt(13)
	v_mov_b32_e32 v64, v18
	s_waitcnt lgkmcnt(12)
	v_mov_b32_e32 v65, v22
	v_pk_fma_f32 v[38:39], v[0:1], v[64:65], v[38:39] op_sel_hi:[0,1,1]
	s_waitcnt lgkmcnt(11)
	v_mov_b32_e32 v64, v42
	s_waitcnt lgkmcnt(10)
	v_mov_b32_e32 v65, v46
	v_pk_fma_f32 v[36:37], v[0:1], v[64:65], v[36:37] op_sel_hi:[0,1,1]
	s_waitcnt lgkmcnt(9)
	v_mov_b32_e32 v64, v50
	s_waitcnt lgkmcnt(8)
	v_mov_b32_e32 v65, v54
	v_pk_fma_f32 v[34:35], v[0:1], v[64:65], v[34:35] op_sel_hi:[0,1,1]
	s_waitcnt lgkmcnt(7)
	v_mov_b32_e32 v64, v58
	s_waitcnt lgkmcnt(6)
	v_mov_b32_e32 v65, v76
	v_pk_fma_f32 v[32:33], v[0:1], v[64:65], v[32:33] op_sel_hi:[0,1,1]
	s_waitcnt lgkmcnt(5)
	v_mov_b32_e32 v64, v80
	s_waitcnt lgkmcnt(4)
	v_mov_b32_e32 v65, v84
	v_pk_fma_f32 v[30:31], v[0:1], v[64:65], v[30:31] op_sel_hi:[0,1,1]
	s_waitcnt lgkmcnt(3)
	v_mov_b32_e32 v64, v88
	s_waitcnt lgkmcnt(2)
	v_mov_b32_e32 v65, v98
	v_pk_fma_f32 v[28:29], v[0:1], v[64:65], v[28:29] op_sel_hi:[0,1,1]
	s_waitcnt lgkmcnt(1)
	v_mov_b32_e32 v64, v102
	s_waitcnt lgkmcnt(0)
	v_mov_b32_e32 v65, v106
	v_pk_fma_f32 v[26:27], v[0:1], v[64:65], v[26:27] op_sel_hi:[0,1,1]
	v_lshl_add_u64 v[64:65], s[18:19], 2, v[74:75]
	s_mul_hi_u32 s19, s14, s11
	s_mul_i32 s18, s14, s11
	v_mov_b32_e32 v106, v103
	v_mov_b32_e32 v98, v89
	v_mov_b32_e32 v84, v81
	v_mov_b32_e32 v76, v59
	v_mov_b32_e32 v54, v51
	v_mov_b32_e32 v46, v43
	v_mov_b32_e32 v22, v19
	s_or_b32 s11, s9, 7
	s_waitcnt vmcnt(15)
; __device__ __forceinline__ void bias_phase(const Params& P, LAS unsigned char* lds, int G) {
;     ...
;         if (j >= 0) { const float* wp = wsrc + (size_t)(wid * 128) * ncol + j;
; #pragma unroll 16
;             for (int k = 0; k < 128; ++k) { const float w = wp[(size_t)k * ncol];
; #pragma unroll
;                 for (int b = 0; b < 16; ++b) a[b] += sC[b * 1024 + wid * 128 + k] * w; } }
	v_mov_b32_e32 v0, v119
	v_lshl_add_u64 v[140:141], s[100:101], 2, v[140:141]
	global_load_dword v119, v[140:141], off
	v_pk_fma_f32 v[10:11], v[0:1], v[14:15], v[40:41] op_sel_hi:[0,1,1]
	v_lshl_add_u64 v[14:15], s[18:19], 2, v[74:75]
	v_pk_fma_f32 v[26:27], v[0:1], v[106:107], v[26:27] op_sel_hi:[0,1,1]
	v_pk_fma_f32 v[28:29], v[0:1], v[98:99], v[28:29] op_sel_hi:[0,1,1]
	v_pk_fma_f32 v[30:31], v[0:1], v[84:85], v[30:31] op_sel_hi:[0,1,1]
	v_pk_fma_f32 v[32:33], v[0:1], v[76:77], v[32:33] op_sel_hi:[0,1,1]
	v_pk_fma_f32 v[34:35], v[0:1], v[54:55], v[34:35] op_sel_hi:[0,1,1]
	v_pk_fma_f32 v[36:37], v[0:1], v[46:47], v[36:37] op_sel_hi:[0,1,1]
	v_pk_fma_f32 v[18:19], v[0:1], v[22:23], v[38:39] op_sel_hi:[0,1,1]
	v_mov_b32_e32 v14, v12
	v_mov_b32_e32 v15, v16
	s_mul_hi_u32 s19, s14, s11
	s_mul_i32 s18, s14, s11
	s_or_b32 s11, s9, 8
	v_mov_b32_e32 v16, v13
	s_waitcnt vmcnt(15)
	v_mov_b32_e32 v0, v120
	v_lshl_add_u64 v[142:143], s[100:101], 2, v[142:143]
	global_load_dword v120, v[142:143], off
	v_pk_fma_f32 v[10:11], v[0:1], v[14:15], v[10:11] op_sel_hi:[0,1,1]
	v_mov_b32_e32 v14, v20
	v_mov_b32_e32 v15, v24
	v_pk_fma_f32 v[38:39], v[0:1], v[14:15], v[18:19] op_sel_hi:[0,1,1]
	v_mov_b32_e32 v14, v44
	v_mov_b32_e32 v15, v48
	v_pk_fma_f32 v[36:37], v[0:1], v[14:15], v[36:37] op_sel_hi:[0,1,1]
	v_mov_b32_e32 v14, v52
	v_mov_b32_e32 v15, v56
	v_pk_fma_f32 v[34:35], v[0:1], v[14:15], v[34:35] op_sel_hi:[0,1,1]
	v_mov_b32_e32 v14, v60
	v_mov_b32_e32 v15, v78
	v_pk_fma_f32 v[32:33], v[0:1], v[14:15], v[32:33] op_sel_hi:[0,1,1]
	v_mov_b32_e32 v14, v82
	v_mov_b32_e32 v15, v86
	v_pk_fma_f32 v[22:23], v[0:1], v[14:15], v[30:31] op_sel_hi:[0,1,1]
	v_mov_b32_e32 v14, v90
	v_mov_b32_e32 v15, v100
	v_pk_fma_f32 v[18:19], v[0:1], v[14:15], v[28:29] op_sel_hi:[0,1,1]
	v_mov_b32_e32 v14, v104
	v_mov_b32_e32 v15, v108
	v_pk_fma_f32 v[14:15], v[0:1], v[14:15], v[26:27] op_sel_hi:[0,1,1]
	v_lshl_add_u64 v[26:27], s[18:19], 2, v[74:75]
	s_mul_hi_u32 s19, s14, s11
	s_mul_i32 s18, s14, s11
	v_mov_b32_e32 v108, v105
	v_mov_b32_e32 v100, v91
	v_mov_b32_e32 v86, v83
	v_mov_b32_e32 v78, v61
	v_mov_b32_e32 v56, v53
	v_mov_b32_e32 v48, v45
	v_mov_b32_e32 v24, v21
	s_or_b32 s11, s9, 9
	s_waitcnt vmcnt(15)
	v_mov_b32_e32 v0, v121
	v_lshl_add_u64 v[144:145], s[100:101], 2, v[144:145]
	global_load_dword v121, v[144:145], off
	v_pk_fma_f32 v[16:17], v[0:1], v[16:17], v[10:11] op_sel_hi:[0,1,1]
	v_lshl_add_u64 v[10:11], s[18:19], 2, v[74:75]
	v_pk_fma_f32 v[14:15], v[0:1], v[108:109], v[14:15] op_sel_hi:[0,1,1]
	v_pk_fma_f32 v[18:19], v[0:1], v[100:101], v[18:19] op_sel_hi:[0,1,1]
	v_pk_fma_f32 v[22:23], v[0:1], v[86:87], v[22:23] op_sel_hi:[0,1,1]
	v_pk_fma_f32 v[26:27], v[0:1], v[78:79], v[32:33] op_sel_hi:[0,1,1]
	v_pk_fma_f32 v[28:29], v[0:1], v[56:57], v[34:35] op_sel_hi:[0,1,1]
	v_pk_fma_f32 v[30:31], v[0:1], v[48:49], v[36:37] op_sel_hi:[0,1,1]
	v_pk_fma_f32 v[20:21], v[0:1], v[24:25], v[38:39] op_sel_hi:[0,1,1]
	ds_read_b128 v[10:13], v62 offset:4128
	ds_read_b128 v[32:35], v62 offset:8224
	ds_read_b128 v[36:39], v62 offset:12320
	ds_read_b128 v[40:43], v62 offset:16416
	ds_read_b128 v[44:47], v62 offset:20512
	ds_read_b128 v[48:51], v62 offset:24608
	ds_read_b128 v[52:55], v62 offset:28704
	ds_read_b128 v[56:59], v62 offset:32800
	ds_read_b128 v[76:79], v62 offset:36896
	ds_read_b128 v[80:83], v62 offset:40992
	ds_read_b128 v[84:87], v62 offset:45088
	ds_read_b128 v[88:91], v62 offset:49184
	ds_read_b128 v[98:101], v62 offset:53280
	ds_read_b128 v[102:105], v62 offset:57376
	ds_read_b128 v[106:109], v62 offset:61472
	v_mov_b32_e32 v24, v6
	s_waitcnt lgkmcnt(14)
	v_mov_b32_e32 v25, v10
	s_mul_hi_u32 s19, s14, s11
	s_mul_i32 s18, s14, s11
	s_or_b32 s11, s9, 10
	v_mov_b32_e32 v10, v7
	s_waitcnt vmcnt(15)
	v_mov_b32_e32 v0, v122
	v_lshl_add_u64 v[146:147], s[100:101], 2, v[146:147]
	global_load_dword v122, v[146:147], off
	v_pk_fma_f32 v[16:17], v[0:1], v[24:25], v[16:17] op_sel_hi:[0,1,1]
	s_waitcnt lgkmcnt(13)
	v_mov_b32_e32 v24, v32
	s_waitcnt lgkmcnt(12)
	v_mov_b32_e32 v25, v36
	v_pk_fma_f32 v[20:21], v[0:1], v[24:25], v[20:21] op_sel_hi:[0,1,1]
	s_waitcnt lgkmcnt(11)
	v_mov_b32_e32 v24, v40
	s_waitcnt lgkmcnt(10)
	v_mov_b32_e32 v25, v44
	v_pk_fma_f32 v[24:25], v[0:1], v[24:25], v[30:31] op_sel_hi:[0,1,1]
	s_waitcnt lgkmcnt(9)
	v_mov_b32_e32 v30, v48
	s_waitcnt lgkmcnt(8)
	v_mov_b32_e32 v31, v52
	v_pk_fma_f32 v[28:29], v[0:1], v[30:31], v[28:29] op_sel_hi:[0,1,1]
	s_waitcnt lgkmcnt(7)
	v_mov_b32_e32 v30, v56
	s_waitcnt lgkmcnt(6)
	v_mov_b32_e32 v31, v76
	v_pk_fma_f32 v[26:27], v[0:1], v[30:31], v[26:27] op_sel_hi:[0,1,1]
	s_waitcnt lgkmcnt(5)
	v_mov_b32_e32 v30, v80
	s_waitcnt lgkmcnt(4)
	v_mov_b32_e32 v31, v84
	v_pk_fma_f32 v[22:23], v[0:1], v[30:31], v[22:23] op_sel_hi:[0,1,1]
	s_waitcnt lgkmcnt(3)
	v_mov_b32_e32 v30, v88
	s_waitcnt lgkmcnt(2)
	v_mov_b32_e32 v31, v98
	v_pk_fma_f32 v[18:19], v[0:1], v[30:31], v[18:19] op_sel_hi:[0,1,1]
	s_waitcnt lgkmcnt(1)
	v_mov_b32_e32 v30, v102
	s_waitcnt lgkmcnt(0)
	v_mov_b32_e32 v31, v106
	v_pk_fma_f32 v[14:15], v[0:1], v[30:31], v[14:15] op_sel_hi:[0,1,1]
	v_lshl_add_u64 v[30:31], s[18:19], 2, v[74:75]
	s_mul_hi_u32 s19, s14, s11
	s_mul_i32 s18, s14, s11
	v_mov_b32_e32 v106, v103
	v_mov_b32_e32 v98, v89
	v_mov_b32_e32 v84, v81
	v_mov_b32_e32 v76, v57
	v_mov_b32_e32 v52, v49
	v_mov_b32_e32 v44, v41
	v_mov_b32_e32 v36, v33
	s_or_b32 s11, s9, 11
	s_waitcnt vmcnt(15)
; __device__ __forceinline__ void bias_phase(const Params& P, LAS unsigned char* lds, int G) {
;     ...
;         if (j >= 0) { const float* wp = wsrc + (size_t)(wid * 128) * ncol + j;
; #pragma unroll 16
;             for (int k = 0; k < 128; ++k) { const float w = wp[(size_t)k * ncol];
; #pragma unroll
;                 for (int b = 0; b < 16; ++b) a[b] += sC[b * 1024 + wid * 128 + k] * w; } }
	v_mov_b32_e32 v0, v123
	v_lshl_add_u64 v[148:149], s[100:101], 2, v[148:149]
	global_load_dword v123, v[148:149], off
	v_pk_fma_f32 v[6:7], v[0:1], v[10:11], v[16:17] op_sel_hi:[0,1,1]
	v_lshl_add_u64 v[10:11], s[18:19], 2, v[74:75]
	v_pk_fma_f32 v[14:15], v[0:1], v[106:107], v[14:15] op_sel_hi:[0,1,1]
	v_pk_fma_f32 v[18:19], v[0:1], v[98:99], v[18:19] op_sel_hi:[0,1,1]
	v_pk_fma_f32 v[22:23], v[0:1], v[84:85], v[22:23] op_sel_hi:[0,1,1]
	v_pk_fma_f32 v[26:27], v[0:1], v[76:77], v[26:27] op_sel_hi:[0,1,1]
	v_pk_fma_f32 v[28:29], v[0:1], v[52:53], v[28:29] op_sel_hi:[0,1,1]
	v_pk_fma_f32 v[24:25], v[0:1], v[44:45], v[24:25] op_sel_hi:[0,1,1]
	v_pk_fma_f32 v[20:21], v[0:1], v[36:37], v[20:21] op_sel_hi:[0,1,1]
	v_mov_b32_e32 v16, v42
	v_mov_b32_e32 v17, v46
	v_mov_b32_e32 v10, v8
	v_mov_b32_e32 v11, v12
	s_mul_hi_u32 s19, s14, s11
	s_mul_i32 s18, s14, s11
	s_or_b32 s11, s9, 12
	v_mov_b32_e32 v12, v9
	v_mov_b32_e32 v46, v43
	v_mov_b32_e32 v98, v2
	s_waitcnt vmcnt(15)
	v_mov_b32_e32 v0, v124
	v_lshl_add_u64 v[150:151], s[100:101], 2, v[150:151]
	global_load_dword v124, v[150:151], off
	v_pk_fma_f32 v[16:17], v[0:1], v[16:17], v[24:25] op_sel_hi:[0,1,1]
	v_mov_b32_e32 v24, v58
	v_mov_b32_e32 v25, v78
	v_pk_fma_f32 v[24:25], v[0:1], v[24:25], v[26:27] op_sel_hi:[0,1,1]
	v_mov_b32_e32 v26, v82
	v_mov_b32_e32 v27, v86
	v_pk_fma_f32 v[22:23], v[0:1], v[26:27], v[22:23] op_sel_hi:[0,1,1]
	v_mov_b32_e32 v26, v90
	v_mov_b32_e32 v27, v100
	v_pk_fma_f32 v[6:7], v[0:1], v[10:11], v[6:7] op_sel_hi:[0,1,1]
	v_mov_b32_e32 v10, v34
	v_mov_b32_e32 v11, v38
	v_pk_fma_f32 v[18:19], v[0:1], v[26:27], v[18:19] op_sel_hi:[0,1,1]
	v_mov_b32_e32 v26, v104
	v_mov_b32_e32 v27, v108
	v_pk_fma_f32 v[10:11], v[0:1], v[10:11], v[20:21] op_sel_hi:[0,1,1]
	v_mov_b32_e32 v20, v50
	v_mov_b32_e32 v21, v54
	v_pk_fma_f32 v[14:15], v[0:1], v[26:27], v[14:15] op_sel_hi:[0,1,1]
	v_lshl_add_u64 v[26:27], s[18:19], 2, v[74:75]
	v_pk_fma_f32 v[20:21], v[0:1], v[20:21], v[28:29] op_sel_hi:[0,1,1]
	v_mov_b32_e32 v86, v83
	v_mov_b32_e32 v78, v59
	s_mul_hi_u32 s19, s14, s11
	s_mul_i32 s18, s14, s11
	v_mov_b32_e32 v108, v105
	v_mov_b32_e32 v100, v91
	v_mov_b32_e32 v54, v51
	v_mov_b32_e32 v38, v35
	s_or_b32 s11, s9, 13
	s_waitcnt vmcnt(15)
	v_mov_b32_e32 v0, v125
	v_lshl_add_u64 v[152:153], s[100:101], 2, v[152:153]
	global_load_dword v125, v[152:153], off
	v_pk_fma_f32 v[88:89], v[0:1], v[86:87], v[22:23] op_sel_hi:[0,1,1]
	v_pk_fma_f32 v[86:87], v[0:1], v[78:79], v[24:25] op_sel_hi:[0,1,1]
	v_pk_fma_f32 v[78:79], v[0:1], v[12:13], v[6:7] op_sel_hi:[0,1,1]
	v_lshl_add_u64 v[6:7], s[18:19], 2, v[74:75]
	v_pk_fma_f32 v[76:77], v[0:1], v[108:109], v[14:15] op_sel_hi:[0,1,1]
	v_pk_fma_f32 v[90:91], v[0:1], v[100:101], v[18:19] op_sel_hi:[0,1,1]
	v_pk_fma_f32 v[84:85], v[0:1], v[54:55], v[20:21] op_sel_hi:[0,1,1]
	v_pk_fma_f32 v[82:83], v[0:1], v[46:47], v[16:17] op_sel_hi:[0,1,1]
	v_pk_fma_f32 v[80:81], v[0:1], v[38:39], v[10:11] op_sel_hi:[0,1,1]
	ds_read_b128 v[6:9], v62 offset:4144
	ds_read_b128 v[10:13], v62 offset:8240
	ds_read_b128 v[14:17], v62 offset:12336
	ds_read_b128 v[18:21], v62 offset:16432
	ds_read_b128 v[22:25], v62 offset:20528
	ds_read_b128 v[26:29], v62 offset:24624
	ds_read_b128 v[30:33], v62 offset:28720
	ds_read_b128 v[34:37], v62 offset:32816
	ds_read_b128 v[38:41], v62 offset:36912
	ds_read_b128 v[42:45], v62 offset:41008
	ds_read_b128 v[46:49], v62 offset:45104
	ds_read_b128 v[50:53], v62 offset:49200
	ds_read_b128 v[54:57], v62 offset:53296
	ds_read_b128 v[58:61], v62 offset:57392
	ds_read_b128 v[62:65], v62 offset:61488
	s_waitcnt lgkmcnt(14)
	v_mov_b32_e32 v99, v6
	s_mul_hi_u32 s19, s14, s11
	s_mul_i32 s18, s14, s11
	s_or_b32 s11, s9, 14
	v_mov_b32_e32 v6, v3
	s_waitcnt vmcnt(15)
	v_mov_b32_e32 v0, v126
	v_lshl_add_u64 v[154:155], s[100:101], 2, v[154:155]
	global_load_dword v126, v[154:155], off
	v_pk_fma_f32 v[78:79], v[0:1], v[98:99], v[78:79] op_sel_hi:[0,1,1]
	s_waitcnt lgkmcnt(13)
	v_mov_b32_e32 v98, v10
	s_waitcnt lgkmcnt(12)
	v_mov_b32_e32 v99, v14
	v_pk_fma_f32 v[80:81], v[0:1], v[98:99], v[80:81] op_sel_hi:[0,1,1]
	s_waitcnt lgkmcnt(11)
	v_mov_b32_e32 v98, v18
	s_waitcnt lgkmcnt(10)
	v_mov_b32_e32 v99, v22
	v_pk_fma_f32 v[82:83], v[0:1], v[98:99], v[82:83] op_sel_hi:[0,1,1]
	s_waitcnt lgkmcnt(9)
	v_mov_b32_e32 v98, v26
	s_waitcnt lgkmcnt(8)
	v_mov_b32_e32 v99, v30
	v_pk_fma_f32 v[84:85], v[0:1], v[98:99], v[84:85] op_sel_hi:[0,1,1]
	s_waitcnt lgkmcnt(7)
	v_mov_b32_e32 v98, v34
	s_waitcnt lgkmcnt(6)
	v_mov_b32_e32 v99, v38
	v_pk_fma_f32 v[86:87], v[0:1], v[98:99], v[86:87] op_sel_hi:[0,1,1]
	s_waitcnt lgkmcnt(5)
	v_mov_b32_e32 v98, v42
	s_waitcnt lgkmcnt(4)
; __device__ __forceinline__ void bias_phase(const Params& P, LAS unsigned char* lds, int G) {
;     ...
;         if (j >= 0) { const float* wp = wsrc + (size_t)(wid * 128) * ncol + j;
; #pragma unroll 16
;             for (int k = 0; k < 128; ++k) { const float w = wp[(size_t)k * ncol];
; #pragma unroll
;                 for (int b = 0; b < 16; ++b) a[b] += sC[b * 1024 + wid * 128 + k] * w; } }
; #pragma unroll
;         for (int b = 0; b < 16; ++b) red[(wid * 16 + b) * 64 + lane] = a[b];
;         __syncthreads();
;         for (int o = tid; o < 1024; o += NTHR) { const int b = o >> 6, ln = o & 63; float s = 0.f;
; #pragma unroll
;             for (int w = 0; w < 8; ++w) s += red[(w * 16 + b) * 64 + ln];
;             if (!ffn) BW1[((size_t)l * 16 + b) * 4096 + R0 + ln] = s; else BW2[((size_t)l * 16 + b) * 5632 + R0 + ln] = s; }
	v_mov_b32_e32 v99, v46
	v_pk_fma_f32 v[88:89], v[0:1], v[98:99], v[88:89] op_sel_hi:[0,1,1]
	s_waitcnt lgkmcnt(3)
	v_mov_b32_e32 v98, v50
	s_waitcnt lgkmcnt(2)
	v_mov_b32_e32 v99, v54
	v_pk_fma_f32 v[90:91], v[0:1], v[98:99], v[90:91] op_sel_hi:[0,1,1]
	s_waitcnt lgkmcnt(1)
	v_mov_b32_e32 v98, v58
	s_waitcnt lgkmcnt(0)
	v_mov_b32_e32 v99, v62
	v_pk_fma_f32 v[76:77], v[0:1], v[98:99], v[76:77] op_sel_hi:[0,1,1]
	v_lshl_add_u64 v[98:99], s[18:19], 2, v[74:75]
	s_mul_hi_u32 s19, s14, s11
	s_mul_i32 s18, s14, s11
	v_mov_b32_e32 v62, v59
	v_mov_b32_e32 v54, v51
	v_mov_b32_e32 v46, v43
	v_mov_b32_e32 v38, v35
	v_mov_b32_e32 v30, v27
	v_mov_b32_e32 v22, v19
	v_mov_b32_e32 v14, v11
	s_or_b32 s11, s9, 15
	s_add_i32 s9, s9, 16
	s_cmpk_lg_i32 s9, 0x80
	s_waitcnt vmcnt(15)
	v_mov_b32_e32 v0, v127
	v_lshl_add_u64 v[156:157], s[100:101], 2, v[156:157]
	global_load_dword v127, v[156:157], off
	v_pk_fma_f32 v[2:3], v[0:1], v[6:7], v[78:79] op_sel_hi:[0,1,1]
	v_lshl_add_u64 v[6:7], s[18:19], 2, v[74:75]
	v_pk_fma_f32 v[58:59], v[0:1], v[62:63], v[76:77] op_sel_hi:[0,1,1]
	v_pk_fma_f32 v[50:51], v[0:1], v[54:55], v[90:91] op_sel_hi:[0,1,1]
	v_pk_fma_f32 v[42:43], v[0:1], v[46:47], v[88:89] op_sel_hi:[0,1,1]
	v_pk_fma_f32 v[34:35], v[0:1], v[38:39], v[86:87] op_sel_hi:[0,1,1]
	v_pk_fma_f32 v[26:27], v[0:1], v[30:31], v[84:85] op_sel_hi:[0,1,1]
	v_pk_fma_f32 v[18:19], v[0:1], v[22:23], v[82:83] op_sel_hi:[0,1,1]
	v_pk_fma_f32 v[10:11], v[0:1], v[14:15], v[80:81] op_sel_hi:[0,1,1]
	v_mov_b32_e32 v14, v28
	v_mov_b32_e32 v15, v32
	v_mov_b32_e32 v6, v4
	v_mov_b32_e32 v7, v8
	s_mul_hi_u32 s19, s14, s11
	s_mul_i32 s18, s14, s11
	v_mov_b32_e32 v32, v29
	v_mov_b32_e32 v8, v5
	s_waitcnt vmcnt(15)
	v_mov_b32_e32 v0, v128
	v_lshl_add_u64 v[158:159], s[100:101], 2, v[158:159]
	global_load_dword v128, v[158:159], off
	v_pk_fma_f32 v[30:31], v[0:1], v[14:15], v[26:27] op_sel_hi:[0,1,1]
	v_mov_b32_e32 v14, v36
	v_mov_b32_e32 v15, v40
	v_pk_fma_f32 v[2:3], v[0:1], v[6:7], v[2:3] op_sel_hi:[0,1,1]
	v_mov_b32_e32 v6, v12
	v_mov_b32_e32 v7, v16
	v_pk_fma_f32 v[26:27], v[0:1], v[14:15], v[34:35] op_sel_hi:[0,1,1]
	v_mov_b32_e32 v14, v44
	v_mov_b32_e32 v15, v48
	v_pk_fma_f32 v[6:7], v[0:1], v[6:7], v[10:11] op_sel_hi:[0,1,1]
	v_mov_b32_e32 v10, v20
	v_mov_b32_e32 v11, v24
	v_pk_fma_f32 v[22:23], v[0:1], v[14:15], v[42:43] op_sel_hi:[0,1,1]
	v_mov_b32_e32 v14, v52
	v_mov_b32_e32 v15, v56
	v_pk_fma_f32 v[10:11], v[0:1], v[10:11], v[18:19] op_sel_hi:[0,1,1]
	v_pk_fma_f32 v[18:19], v[0:1], v[14:15], v[50:51] op_sel_hi:[0,1,1]
	v_mov_b32_e32 v14, v60
	v_mov_b32_e32 v15, v64
	v_lshl_add_u64 v[34:35], s[18:19], 2, v[74:75]
	v_pk_fma_f32 v[14:15], v[0:1], v[14:15], v[58:59] op_sel_hi:[0,1,1]
	v_mov_b32_e32 v64, v61
	v_mov_b32_e32 v56, v53
	v_mov_b32_e32 v48, v45
	v_mov_b32_e32 v40, v37
	v_mov_b32_e32 v24, v21
	v_mov_b32_e32 v16, v13
	s_waitcnt vmcnt(15)
	v_mov_b32_e32 v0, v129
	v_lshl_add_u64 v[160:161], s[100:101], 2, v[160:161]
	global_load_dword v129, v[160:161], off
	v_pk_fma_f32 v[14:15], v[0:1], v[64:65], v[14:15] op_sel_hi:[0,1,1]
	v_pk_fma_f32 v[18:19], v[0:1], v[56:57], v[18:19] op_sel_hi:[0,1,1]
	v_pk_fma_f32 v[22:23], v[0:1], v[48:49], v[22:23] op_sel_hi:[0,1,1]
	v_pk_fma_f32 v[26:27], v[0:1], v[40:41], v[26:27] op_sel_hi:[0,1,1]
	v_pk_fma_f32 v[28:29], v[0:1], v[32:33], v[30:31] op_sel_hi:[0,1,1]
	v_pk_fma_f32 v[20:21], v[0:1], v[24:25], v[10:11] op_sel_hi:[0,1,1]
	v_pk_fma_f32 v[16:17], v[0:1], v[16:17], v[6:7] op_sel_hi:[0,1,1]
	v_pk_fma_f32 v[24:25], v[0:1], v[8:9], v[2:3] op_sel_hi:[0,1,1]
	s_cbranch_scc1 .LBB0_651
.LBB0_652:
	s_waitcnt vmcnt(0)
	s_or_b64 exec, exec, s[16:17]
	v_add_u32_e32 v0, s51, v69
	ds_write2st64_b32 v0, v24, v25 offset1:1
	ds_write2st64_b32 v0, v16, v17 offset0:2 offset1:3
	ds_write2st64_b32 v0, v20, v21 offset0:4 offset1:5
	ds_write2st64_b32 v0, v28, v29 offset0:6 offset1:7
	ds_write2st64_b32 v0, v26, v27 offset0:8 offset1:9
	ds_write2st64_b32 v0, v22, v23 offset0:10 offset1:11
	ds_write2st64_b32 v0, v18, v19 offset0:12 offset1:13
	ds_write2st64_b32 v0, v14, v15 offset0:14 offset1:15
	s_waitcnt lgkmcnt(0)
	s_barrier
	s_and_saveexec_b64 s[14:15], s[42:43]
	s_cbranch_execz .LBB0_623
	s_ashr_i32 s9, s8, 31
	s_ashr_i32 s13, s12, 31
	s_lshl_b64 s[16:17], s[8:9], 18
	s_add_u32 s11, s37, s16
	s_addc_u32 s16, s48, s17
	s_lshl_b64 s[12:13], s[12:13], 2
	s_add_u32 s12, s11, s12
	s_addc_u32 s13, s16, s13
	s_ashr_i32 s11, s10, 31
	v_mov_b32_e32 v73, v1
	s_lshl_b64 s[8:9], s[8:9], 4
	v_lshl_add_u64 v[2:3], s[12:13], 0, v[72:73]
	v_lshl_add_u64 v[4:5], s[10:11], 2, v[70:71]
	s_mov_b64 s[10:11], 0
	v_mov_b32_e32 v0, v66
	s_branch .LBB0_655
